# dead-code elimination in HGRN state-only pass: Qt/Kt decay products and their LDS stores are never read there
# speedup vs baseline: 1.0075x; 1.0075x over previous
; #define LAS __attribute__((address_space(3)))
; __device__ __forceinline__ unsigned cvt_pk_bf16(float lo, float hi) { unsigned r; asm volatile("v_cvt_pk_bf16_f32 %0, %1, %2" : "=v"(r) : "v"(lo), "v"(hi)); return r; }
; __device__ __forceinline__ float bf2f(unsigned short b) { return __uint_as_float(((unsigned)b) << 16); }
; template <bool FULL>
; __device__ __forceinline__ void hgrn_item(LAS unsigned char* lds, const bf16_t* P, bf16_t* AB, int L, int hd, const float* lbv, const float* anorm, const float* S0, const float* Dd, int ns, float* Sout, float* Dout) {
;     ...
;         {
;             float run = 0.f;
; #pragma unroll
;             for (int i = 0; i < 4; ++i) { float z = bf2f(zc[i]); z = fminf(fmaxf(z, -30.f), 30.f); const float e = __expf(-z), sg = __builtin_amdgcn_rcpf(1.f + e), sn = e * sg;
;                 const float f = lb + oml * sg; run += __builtin_amdgcn_logf(f) * 0.69314718056f; cs[i] = run; kk[i] = oml * sn; qv[i] = bf2f(qc[i]); }
;             qsum[tq * 128 + k] = run;
;         }
;         __syncthreads();
;         {
;             float pre = 0.f, tot = 0.f;
; #pragma unroll
;             for (int j = 0; j < 4; ++j) { const float v = qsum[j * 128 + k]; tot += v; pre += (j < tq) ? v : 0.f; }
;             btot += tot;
;             float kh[4];
; #pragma unroll
;             for (int i = 0; i < 4; ++i) { const float b = pre + cs[i]; const float qt = qv[i] * __expf(b), kt = kk[i] * __expf(fminf(-b, 80.f)); kh[i] = kk[i] * __expf(tot - b);
;                 Qt[(4 * tq + i) * 136 + k] = (bf16_t)(cvt_pk_bf16(qt, 0.f) & 0xffffu); Kt[(4 * tq + i) * 136 + k] = (bf16_t)(cvt_pk_bf16(kt, 0.f) & 0xffffu); }
;             u32x2 kp; kp.x = cvt_pk_bf16(kh[0], kh[1]); kp.y = cvt_pk_bf16(kh[2], kh[3]);
;             *(LAS u32x2*)(KhT + k * 20 + 4 * tq) = kp;
;             if (tq == 0) dvec[k] = __expf(tot);
.LBB0_227:
	s_or_b64 exec, exec, s[4:5]
	v_lshlrev_b32_e32 v68, 16, v68
	v_max_f32_e32 v68, v68, v68
	v_med3_f32 v68, v68, s29, v225
	v_lshlrev_b32_e32 v72, 16, v72
	v_mul_f32_e32 v68, 0xbfb8aa3b, v68
	v_max_f32_e32 v72, v72, v72
	v_lshlrev_b32_e32 v70, 16, v70
	v_exp_f32_e32 v68, v68
	v_med3_f32 v72, v72, s29, v225
	v_max_f32_e32 v70, v70, v70
	v_mul_f32_e32 v72, 0xbfb8aa3b, v72
	v_med3_f32 v70, v70, s29, v225
	v_lshlrev_b32_e32 v47, 16, v47
	v_exp_f32_e32 v72, v72
	v_mul_f32_e32 v70, 0xbfb8aa3b, v70
	v_max_f32_e32 v47, v47, v47
	v_exp_f32_e32 v70, v70
	v_add_f32_e32 v69, 1.0, v68
	v_med3_f32 v47, v47, s29, v225
	v_rcp_f32_e32 v69, v69
	v_mul_f32_e32 v47, 0xbfb8aa3b, v47
	v_exp_f32_e32 v47, v47
	v_add_f32_e32 v73, 1.0, v72
	v_rcp_f32_e32 v73, v73
	v_lshlrev_b32_e32 v74, 16, v71
	v_add_f32_e32 v71, 1.0, v70
	v_rcp_f32_e32 v71, v71
	v_mul_f32_e32 v68, v68, v69
	v_mul_f32_e32 v78, v55, v68
	v_add_f32_e32 v68, 1.0, v47
	v_rcp_f32_e32 v68, v68
	v_mul_f32_e32 v72, v72, v73
	v_fma_f32 v73, v55, v73, v53
	v_log_f32_e32 v73, v73
	v_mul_f32_e32 v70, v70, v71
	v_fma_f32 v71, v55, v71, v53
	v_log_f32_e32 v71, v71
	v_fma_f32 v69, v55, v69, v53
	v_log_f32_e32 v69, v69
	v_mul_f32_e32 v47, v47, v68
	v_fma_f32 v68, v55, v68, v53
	v_log_f32_e32 v68, v68
	v_fma_f32 v73, v73, s30, 0
	v_fmamk_f32 v75, v71, 0x3f317218, v73
	v_mul_f32_e32 v79, v55, v47
	v_fmamk_f32 v47, v69, 0x3f317218, v75
	v_fmamk_f32 v81, v68, 0x3f317218, v47
	ds_write_b32 v54, v81 offset:19456
	s_waitcnt lgkmcnt(0)
	s_barrier
	ds_read2st64_b32 v[68:69], v49 offset0:76 offset1:78
	ds_read2st64_b32 v[128:129], v49 offset0:80 offset1:82
	v_mul_f32_e32 v76, v55, v70
	v_mul_f32_e32 v72, v55, v72
	s_waitcnt lgkmcnt(1)
	v_add_f32_e32 v46, 0, v68
	v_cndmask_b32_e64 v68, 0, v46, s[46:47]
	v_add_f32_e32 v46, v46, v69
	v_cndmask_b32_e64 v69, 0, v69, s[44:45]
	v_add_f32_e32 v70, v68, v69
	s_waitcnt lgkmcnt(0)
	v_mov_b32_e32 v68, v128
	v_mov_b32_e32 v69, v129
	v_add_f32_e32 v46, v46, v68
	v_cndmask_b32_e64 v68, 0, v68, s[42:43]
	v_add_f32_e32 v68, v70, v68
	v_cndmask_b32_e64 v70, 0, v69, s[40:41]
	v_add_f32_e32 v71, v68, v70
	v_add_f32_e32 v68, v73, v71
	v_mul_f32_e32 v70, 0x3fb8aa3b, v68
	v_exp_f32_e32 v70, v70
	s_nop 0
	v_mul_f32_e32 v73, v70, v74
	s_nop 0
	v_mov_b32_e32 v70, v69
	v_pk_add_f32 v[46:47], v[46:47], v[70:71]
	v_sub_f32_e32 v68, v46, v68
	v_mul_f32_e32 v68, 0x3fb8aa3b, v68
	v_exp_f32_e32 v68, v68
	v_add_f32_e32 v69, v75, v71
	v_mul_f32_e32 v68, v72, v68
	v_sub_f32_e32 v69, v46, v69
	v_mul_f32_e32 v69, 0x3fb8aa3b, v69
	v_exp_f32_e32 v69, v69
	v_sub_f32_e32 v47, v46, v47
	v_add_f32_e32 v67, v81, v71
	v_sub_f32_e32 v67, v46, v67
	v_mul_f32_e32 v47, 0x3fb8aa3b, v47
	v_mul_f32_e32 v67, 0x3fb8aa3b, v67
	v_exp_f32_e32 v47, v47
	v_exp_f32_e32 v67, v67
	v_mul_f32_e32 v69, v76, v69
	v_mul_f32_e32 v47, v78, v47
	v_mul_f32_e32 v67, v79, v67
	v_cvt_pk_bf16_f32 v68, v68, v69
	v_cvt_pk_bf16_f32 v69, v47, v67
	ds_write_b64 v52, v[68:69] offset:8704
	s_and_saveexec_b64 s[4:5], s[38:39]
	s_cbranch_execz .LBB0_229
	v_mul_f32_e32 v47, 0x3fb8aa3b, v46
	v_exp_f32_e32 v47, v47
	ds_write_b32 v49, v47 offset:18944
